# stack + P0 xor-16/32 wave-sum steps via v_permlane16/32_swap (no LDS round trips left in the row loop)
# baseline (speedup 1.0000x reference)
.LBB0_115:
	v_mul_f32_e32 v221, v61, v61
	v_mul_f32_e32 v222, v63, v63
	v_fmac_f32_e32 v221, v60, v60
	v_fmac_f32_e32 v222, v62, v62
	v_add_f32_e32 v221, v221, v222
	v_mul_f32_e32 v222, v57, v57
	s_waitcnt lgkmcnt(7)
	v_mul_f32_e32 v234, v59, v59
	v_fmac_f32_e32 v222, v56, v56
	v_fmac_f32_e32 v234, v58, v58
	v_add_f32_e32 v222, v222, v234
	v_add_f32_e32 v221, v221, v222
	v_mul_f32_e32 v222, v53, v53
	v_mul_f32_e32 v234, v55, v55
	v_fmac_f32_e32 v222, v52, v52
	v_fmac_f32_e32 v234, v54, v54
	v_add_f32_e32 v222, v222, v234
	v_add_f32_e32 v221, v221, v222
	v_mul_f32_e32 v222, v49, v49
	v_mul_f32_e32 v234, v51, v51
	v_fmac_f32_e32 v222, v48, v48
	v_fmac_f32_e32 v234, v50, v50
	v_add_f32_e32 v222, v222, v234
	v_add_f32_e32 v221, v221, v222
	s_nop 1
	v_mov_b32_dpp v222, v221 quad_perm:[1,0,3,2] row_mask:0xf bank_mask:0xf
	s_waitcnt lgkmcnt(7)
	v_mul_f32_e32 v234, v61, v65
	v_mul_f32_e32 v235, v63, v67
	v_fmac_f32_e32 v234, v60, v64
	v_fmac_f32_e32 v235, v62, v66
	s_waitcnt lgkmcnt(0)
	v_add_f32_e32 v221, v221, v222
	s_nop 1
	v_mov_b32_dpp v222, v221 quad_perm:[2,3,0,1] row_mask:0xf bank_mask:0xf
	v_add_f32_e32 v234, v234, v235
	v_mul_f32_e32 v235, v57, v69
	v_mul_f32_e32 v236, v59, v71
	v_fmac_f32_e32 v235, v56, v68
	s_waitcnt lgkmcnt(0)
	v_add_f32_e32 v221, v221, v222
	s_nop 1
	v_mov_b32_dpp v222, v221 row_half_mirror row_mask:0xf bank_mask:0xf
	v_fmac_f32_e32 v236, v58, v70
	v_add_f32_e32 v234, 0, v234
	v_add_f32_e32 v235, v235, v236
	v_add_f32_e32 v234, v234, v235
	s_waitcnt lgkmcnt(0)
	v_add_f32_e32 v221, v221, v222
	v_mul_f32_e32 v235, v53, v73
	v_mul_f32_e32 v236, v55, v75
	v_mov_b32_dpp v222, v221 row_mirror row_mask:0xf bank_mask:0xf
	v_fmac_f32_e32 v235, v52, v72
	v_fmac_f32_e32 v236, v54, v74
	v_add_f32_e32 v235, v235, v236
	v_add_f32_e32 v234, v234, v235
	v_mul_f32_e32 v235, v49, v77
	v_mul_f32_e32 v236, v51, v79
	v_fmac_f32_e32 v235, v48, v76
	v_fmac_f32_e32 v236, v50, v78
	v_add_f32_e32 v235, v235, v236
	s_waitcnt lgkmcnt(0)
	v_add_f32_e32 v221, v221, v222
	v_add_f32_e32 v234, v234, v235
	v_mul_f32_e32 v236, v61, v81
	v_mul_f32_e32 v237, v63, v83
	v_mov_b32_e32 v222, v221
	s_nop 1
	v_permlane16_swap_b32_e32 v222, v221
	v_mov_b32_dpp v235, v234 quad_perm:[1,0,3,2] row_mask:0xf bank_mask:0xf
	v_fmac_f32_e32 v236, v60, v80
	v_fmac_f32_e32 v237, v62, v82
	v_add_f32_e32 v236, v236, v237
	v_mul_f32_e32 v237, v57, v85
	v_mul_f32_e32 v238, v59, v87
	v_fmac_f32_e32 v237, v56, v84
	v_fmac_f32_e32 v238, v58, v86
	v_add_f32_e32 v236, 0, v236
	v_add_f32_e32 v237, v237, v238
	v_add_f32_e32 v236, v236, v237
	v_mul_f32_e32 v237, v53, v89
	v_mul_f32_e32 v238, v55, v91
	v_fmac_f32_e32 v237, v52, v88
	v_fmac_f32_e32 v238, v54, v90
	s_waitcnt lgkmcnt(0)
	v_add_f32_e32 v221, v221, v222
	s_waitcnt lgkmcnt(0)
	v_add_f32_e32 v234, v234, v235
	v_add_f32_e32 v237, v237, v238
	v_mov_b32_e32 v222, v221
	s_nop 1
	v_permlane32_swap_b32_e32 v222, v221
	v_mov_b32_dpp v235, v234 quad_perm:[2,3,0,1] row_mask:0xf bank_mask:0xf
	v_add_f32_e32 v236, v236, v237
	v_mul_f32_e32 v237, v49, v93
	v_mul_f32_e32 v238, v51, v95
	v_fmac_f32_e32 v237, v48, v92
	v_fmac_f32_e32 v238, v50, v94
	v_add_f32_e32 v237, v237, v238
	v_add_f32_e32 v236, v236, v237
	s_nop 1
	v_mov_b32_dpp v237, v236 quad_perm:[1,0,3,2] row_mask:0xf bank_mask:0xf
	s_waitcnt lgkmcnt(0)
	v_add_f32_e32 v221, v221, v222
	s_waitcnt lgkmcnt(0)
	v_add_f32_e32 v222, v234, v235
	s_nop 1
	v_mov_b32_dpp v234, v222 row_half_mirror row_mask:0xf bank_mask:0xf
	v_fmamk_f32 v221, v221, 0x3a800000, v209
	s_waitcnt lgkmcnt(0)
	v_add_f32_e32 v236, v236, v237
	s_nop 1
	v_mov_b32_dpp v237, v236 quad_perm:[2,3,0,1] row_mask:0xf bank_mask:0xf
	v_cmp_gt_f32_e64 s[0:1], s27, v221
	s_waitcnt lgkmcnt(0)
	v_add_f32_e32 v222, v222, v234
	s_nop 1
	v_mov_b32_dpp v234, v222 row_mirror row_mask:0xf bank_mask:0xf
	v_mul_f32_e32 v238, v63, v99
	s_waitcnt lgkmcnt(0)
	v_add_f32_e32 v235, v236, v237
	v_mul_f32_e32 v237, 0x4b800000, v221
	v_cndmask_b32_e64 v221, v221, v237, s[0:1]
	s_waitcnt lgkmcnt(0)
	v_add_f32_e32 v234, v222, v234
	v_rsq_f32_e32 v221, v221
	v_mov_b32_e32 v237, v234
	s_nop 1
	v_permlane16_swap_b32_e32 v237, v234
	v_fmac_f32_e32 v238, v62, v98
	v_mul_f32_e32 v239, v59, v103
	v_mul_f32_e32 v222, 0x45800000, v221
	v_cndmask_b32_e64 v222, v221, v222, s[0:1]
	s_waitcnt lgkmcnt(0)
	v_add_f32_e32 v221, v234, v237
	v_mul_f32_e32 v237, v61, v97
	v_fmac_f32_e32 v237, v60, v96
	v_add_f32_e32 v237, v237, v238
	v_mul_f32_e32 v238, v57, v101
	v_fmac_f32_e32 v238, v56, v100
	v_fmac_f32_e32 v239, v58, v102
	v_add_f32_e32 v237, 0, v237
	v_add_f32_e32 v238, v238, v239
	v_add_f32_e32 v237, v237, v238
	v_mul_f32_e32 v238, v53, v105
	v_mul_f32_e32 v239, v55, v107
	v_fmac_f32_e32 v238, v52, v104
	v_fmac_f32_e32 v239, v54, v106
	v_add_f32_e32 v238, v238, v239
	v_add_f32_e32 v237, v237, v238
	v_mul_f32_e32 v238, v49, v109
	v_mul_f32_e32 v239, v51, v111
	v_fmac_f32_e32 v238, v48, v108
	v_fmac_f32_e32 v239, v50, v110
	v_add_f32_e32 v238, v238, v239
	v_mul_f32_e32 v239, v61, v113
	v_mul_f32_e32 v240, v63, v115
	v_fmac_f32_e32 v239, v60, v112
	v_fmac_f32_e32 v240, v62, v114
	v_add_f32_e32 v239, v239, v240
	v_mul_f32_e32 v240, v57, v117
	v_mul_f32_e32 v241, v59, v119
	v_fmac_f32_e32 v240, v56, v116
	v_fmac_f32_e32 v241, v58, v118
	v_add_f32_e32 v239, 0, v239
	v_add_f32_e32 v240, v240, v241
	v_add_f32_e32 v239, v239, v240
	v_mul_f32_e32 v240, v53, v121
	v_mul_f32_e32 v241, v55, v123
	v_fmac_f32_e32 v240, v52, v120
	v_fmac_f32_e32 v241, v54, v122
	v_add_f32_e32 v240, v240, v241
	v_add_f32_e32 v239, v239, v240
	v_mul_f32_e32 v240, v49, v125
	v_mul_f32_e32 v241, v51, v127
	v_fmac_f32_e32 v240, v48, v124
	v_fmac_f32_e32 v241, v50, v126
	v_add_f32_e32 v240, v240, v241
	v_mul_f32_e32 v241, v61, v129
	v_mul_f32_e32 v242, v63, v131
	v_fmac_f32_e32 v241, v60, v128
	v_fmac_f32_e32 v242, v62, v130
	v_add_f32_e32 v241, v241, v242
	v_mul_f32_e32 v242, v57, v133
	v_mul_f32_e32 v243, v59, v135
	v_fmac_f32_e32 v242, v56, v132
	v_fmac_f32_e32 v243, v58, v134
	v_add_f32_e32 v241, 0, v241
	v_add_f32_e32 v242, v242, v243
	v_add_f32_e32 v241, v241, v242
	v_mul_f32_e32 v242, v53, v137
	v_mul_f32_e32 v243, v55, v139
	v_fmac_f32_e32 v242, v52, v136
	v_fmac_f32_e32 v243, v54, v138
	v_add_f32_e32 v242, v242, v243
	v_add_f32_e32 v241, v241, v242
	v_mul_f32_e32 v242, v49, v141
	v_mul_f32_e32 v243, v51, v143
	v_fmac_f32_e32 v242, v48, v140
	v_fmac_f32_e32 v243, v50, v142
	v_add_f32_e32 v242, v242, v243
	v_mul_f32_e32 v243, v61, v145
	v_mul_f32_e32 v244, v63, v147
	v_fmac_f32_e32 v243, v60, v144
	v_fmac_f32_e32 v244, v62, v146
	v_add_f32_e32 v243, v243, v244
	v_mul_f32_e32 v244, v57, v149
	v_mul_f32_e32 v245, v59, v151
	v_fmac_f32_e32 v244, v56, v148
	v_fmac_f32_e32 v245, v58, v150
	v_add_f32_e32 v243, 0, v243
	v_add_f32_e32 v244, v244, v245
	v_add_f32_e32 v243, v243, v244
	v_mul_f32_e32 v244, v53, v153
	v_mul_f32_e32 v245, v55, v155
	v_fmac_f32_e32 v244, v52, v152
	v_fmac_f32_e32 v245, v54, v154
	v_add_f32_e32 v244, v244, v245
	v_add_f32_e32 v243, v243, v244
	v_mul_f32_e32 v244, v49, v157
	v_mul_f32_e32 v245, v51, v159
	v_fmac_f32_e32 v244, v48, v156
	v_fmac_f32_e32 v245, v50, v158
	v_add_f32_e32 v244, v244, v245
	v_mul_f32_e32 v245, v61, v161
	v_mul_f32_e32 v246, v63, v163
	v_fmac_f32_e32 v245, v60, v160
	v_fmac_f32_e32 v246, v62, v162
	v_add_f32_e32 v245, v245, v246
	v_mul_f32_e32 v246, v57, v165
	v_mul_f32_e32 v247, v59, v167
	v_fmac_f32_e32 v246, v56, v164
	v_fmac_f32_e32 v247, v58, v166
	v_add_f32_e32 v245, 0, v245
	v_add_f32_e32 v246, v246, v247
	v_add_f32_e32 v245, v245, v246
	v_mul_f32_e32 v246, v53, v169
	v_mul_f32_e32 v247, v55, v171
	v_fmac_f32_e32 v246, v52, v168
	v_fmac_f32_e32 v247, v54, v170
	v_add_f32_e32 v246, v246, v247
	v_add_f32_e32 v245, v245, v246
	v_mul_f32_e32 v246, v49, v173
	v_mul_f32_e32 v247, v51, v175
	v_fmac_f32_e32 v246, v48, v172
	v_fmac_f32_e32 v247, v50, v174
	v_add_f32_e32 v246, v246, v247
	v_mul_f32_e32 v247, v61, v177
	v_mul_f32_e32 v248, v63, v179
	v_fmac_f32_e32 v247, v60, v176
	v_fmac_f32_e32 v248, v62, v178
	v_add_f32_e32 v247, v247, v248
	v_mul_f32_e32 v248, v57, v181
	v_mul_f32_e32 v249, v59, v183
	v_fmac_f32_e32 v248, v56, v180
	v_fmac_f32_e32 v249, v58, v182
	v_add_f32_e32 v247, 0, v247
	v_add_f32_e32 v248, v248, v249
	v_add_f32_e32 v247, v247, v248
	v_mul_f32_e32 v248, v53, v185
	v_mul_f32_e32 v249, v55, v187
	v_fmac_f32_e32 v248, v52, v184
	v_fmac_f32_e32 v249, v54, v186
	v_add_f32_e32 v248, v248, v249
	v_add_f32_e32 v247, v247, v248
	v_mul_f32_e32 v248, v49, v189
	v_mul_f32_e32 v249, v51, v191
	v_fmac_f32_e32 v248, v48, v188
	v_fmac_f32_e32 v249, v50, v190
	v_add_f32_e32 v248, v248, v249
	v_add_f32_e32 v237, v237, v238
	v_add_f32_e32 v239, v239, v240
	v_add_f32_e32 v241, v241, v242
	v_add_f32_e32 v243, v243, v244
	v_add_f32_e32 v245, v245, v246
	v_add_f32_e32 v247, v247, v248
	v_mov_b32_dpp v238, v237 quad_perm:[1,0,3,2] row_mask:0xf bank_mask:0xf
	v_mov_b32_dpp v240, v239 quad_perm:[1,0,3,2] row_mask:0xf bank_mask:0xf
	v_mov_b32_dpp v242, v241 quad_perm:[1,0,3,2] row_mask:0xf bank_mask:0xf
	v_mov_b32_dpp v244, v243 quad_perm:[1,0,3,2] row_mask:0xf bank_mask:0xf
	v_mov_b32_dpp v246, v245 quad_perm:[1,0,3,2] row_mask:0xf bank_mask:0xf
	v_mov_b32_dpp v248, v247 quad_perm:[1,0,3,2] row_mask:0xf bank_mask:0xf
	s_waitcnt lgkmcnt(0)
	v_add_f32_e32 v237, v237, v238
	s_waitcnt lgkmcnt(0)
	v_add_f32_e32 v239, v239, v240
	s_waitcnt lgkmcnt(0)
	v_add_f32_e32 v241, v241, v242
	s_waitcnt lgkmcnt(0)
	v_add_f32_e32 v243, v243, v244
	s_waitcnt lgkmcnt(0)
	v_add_f32_e32 v245, v245, v246
	s_waitcnt lgkmcnt(0)
	v_add_f32_e32 v247, v247, v248
	v_mov_b32_dpp v238, v237 quad_perm:[2,3,0,1] row_mask:0xf bank_mask:0xf
	v_mov_b32_dpp v240, v239 quad_perm:[2,3,0,1] row_mask:0xf bank_mask:0xf
	v_mov_b32_dpp v242, v241 quad_perm:[2,3,0,1] row_mask:0xf bank_mask:0xf
	v_mov_b32_dpp v244, v243 quad_perm:[2,3,0,1] row_mask:0xf bank_mask:0xf
	v_mov_b32_dpp v246, v245 quad_perm:[2,3,0,1] row_mask:0xf bank_mask:0xf
	v_mov_b32_dpp v248, v247 quad_perm:[2,3,0,1] row_mask:0xf bank_mask:0xf
	s_waitcnt lgkmcnt(0)
	v_add_f32_e32 v237, v237, v238
	s_waitcnt lgkmcnt(0)
	v_add_f32_e32 v239, v239, v240
	s_waitcnt lgkmcnt(0)
	v_add_f32_e32 v241, v241, v242
	s_waitcnt lgkmcnt(0)
	v_add_f32_e32 v243, v243, v244
	s_waitcnt lgkmcnt(0)
	v_add_f32_e32 v245, v245, v246
	s_waitcnt lgkmcnt(0)
	v_add_f32_e32 v247, v247, v248
	v_mov_b32_dpp v236, v235 row_half_mirror row_mask:0xf bank_mask:0xf
	v_mov_b32_dpp v238, v237 row_half_mirror row_mask:0xf bank_mask:0xf
	v_mov_b32_dpp v240, v239 row_half_mirror row_mask:0xf bank_mask:0xf
	v_mov_b32_dpp v242, v241 row_half_mirror row_mask:0xf bank_mask:0xf
	v_mov_b32_dpp v244, v243 row_half_mirror row_mask:0xf bank_mask:0xf
	v_mov_b32_dpp v246, v245 row_half_mirror row_mask:0xf bank_mask:0xf
	v_mov_b32_dpp v248, v247 row_half_mirror row_mask:0xf bank_mask:0xf
	s_waitcnt lgkmcnt(0)
	v_add_f32_e32 v235, v235, v236
	s_waitcnt lgkmcnt(0)
	v_add_f32_e32 v237, v237, v238
	s_waitcnt lgkmcnt(0)
	v_add_f32_e32 v239, v239, v240
	s_waitcnt lgkmcnt(0)
	v_add_f32_e32 v241, v241, v242
	s_waitcnt lgkmcnt(0)
	v_add_f32_e32 v243, v243, v244
	s_waitcnt lgkmcnt(0)
	v_add_f32_e32 v245, v245, v246
	s_waitcnt lgkmcnt(0)
	v_add_f32_e32 v247, v247, v248
	v_mov_b32_dpp v236, v235 row_mirror row_mask:0xf bank_mask:0xf
	v_mov_b32_dpp v238, v237 row_mirror row_mask:0xf bank_mask:0xf
	v_mov_b32_dpp v240, v239 row_mirror row_mask:0xf bank_mask:0xf
	v_mov_b32_dpp v242, v241 row_mirror row_mask:0xf bank_mask:0xf
	v_mov_b32_dpp v244, v243 row_mirror row_mask:0xf bank_mask:0xf
	v_mov_b32_dpp v246, v245 row_mirror row_mask:0xf bank_mask:0xf
	v_mov_b32_dpp v248, v247 row_mirror row_mask:0xf bank_mask:0xf
	s_waitcnt lgkmcnt(0)
	v_add_f32_e32 v235, v235, v236
	s_waitcnt lgkmcnt(0)
	v_add_f32_e32 v237, v237, v238
	s_waitcnt lgkmcnt(0)
	v_add_f32_e32 v239, v239, v240
	s_waitcnt lgkmcnt(0)
	v_add_f32_e32 v241, v241, v242
	s_waitcnt lgkmcnt(0)
	v_add_f32_e32 v243, v243, v244
	s_waitcnt lgkmcnt(0)
	v_add_f32_e32 v245, v245, v246
	s_waitcnt lgkmcnt(0)
	v_add_f32_e32 v247, v247, v248
	v_mov_b32_e32 v236, v235
	s_nop 1
	v_permlane16_swap_b32_e32 v236, v235
	v_mov_b32_e32 v238, v237
	s_nop 1
	v_permlane16_swap_b32_e32 v238, v237
	v_mov_b32_e32 v240, v239
	s_nop 1
	v_permlane16_swap_b32_e32 v240, v239
	v_mov_b32_e32 v242, v241
	s_nop 1
	v_permlane16_swap_b32_e32 v242, v241
	v_mov_b32_e32 v244, v243
	s_nop 1
	v_permlane16_swap_b32_e32 v244, v243
	v_mov_b32_e32 v246, v245
	s_nop 1
	v_permlane16_swap_b32_e32 v246, v245
	v_mov_b32_e32 v248, v247
	s_nop 1
	v_permlane16_swap_b32_e32 v248, v247
	s_waitcnt lgkmcnt(0)
	v_add_f32_e32 v235, v235, v236
	s_waitcnt lgkmcnt(0)
	v_add_f32_e32 v237, v237, v238
	s_waitcnt lgkmcnt(0)
	v_add_f32_e32 v239, v239, v240
	s_waitcnt lgkmcnt(0)
	v_add_f32_e32 v241, v241, v242
	s_waitcnt lgkmcnt(0)
	v_add_f32_e32 v243, v243, v244
	s_waitcnt lgkmcnt(0)
	v_add_f32_e32 v245, v245, v246
	s_waitcnt lgkmcnt(0)
	v_add_f32_e32 v247, v247, v248
	v_mov_b32_e32 v234, v221
	s_nop 1
	v_permlane32_swap_b32_e32 v234, v221
	v_mov_b32_e32 v236, v235
	s_nop 1
	v_permlane32_swap_b32_e32 v236, v235
	v_mov_b32_e32 v238, v237
	s_nop 1
	v_permlane32_swap_b32_e32 v238, v237
	v_mov_b32_e32 v240, v239
	s_nop 1
	v_permlane32_swap_b32_e32 v240, v239
	v_mov_b32_e32 v242, v241
	s_nop 1
	v_permlane32_swap_b32_e32 v242, v241
	v_mov_b32_e32 v244, v243
	s_nop 1
	v_permlane32_swap_b32_e32 v244, v243
	v_mov_b32_e32 v246, v245
	s_nop 1
	v_permlane32_swap_b32_e32 v246, v245
	v_mov_b32_e32 v248, v247
	s_nop 1
	v_permlane32_swap_b32_e32 v248, v247
	s_ashr_i32 s69, s68, 31
	v_pk_mul_f32 v[62:63], v[18:19], v[62:63]
	v_pk_mul_f32 v[60:61], v[16:17], v[60:61]
	v_pk_mul_f32 v[58:59], v[22:23], v[58:59]
	v_pk_mul_f32 v[56:57], v[20:21], v[56:57]
	v_pk_mul_f32 v[54:55], v[26:27], v[54:55]
	v_pk_mul_f32 v[52:53], v[24:25], v[52:53]
	v_pk_mul_f32 v[50:51], v[30:31], v[50:51]
	v_pk_mul_f32 v[48:49], v[28:29], v[48:49]
	s_lshl_b64 s[0:1], s[68:69], 11
	v_pk_mul_f32 v[62:63], v[62:63], v[222:223] op_sel_hi:[1,0]
	v_pk_mul_f32 v[60:61], v[60:61], v[222:223] op_sel_hi:[1,0]
	v_pk_mul_f32 v[58:59], v[58:59], v[222:223] op_sel_hi:[1,0]
	v_pk_mul_f32 v[56:57], v[56:57], v[222:223] op_sel_hi:[1,0]
	v_pk_mul_f32 v[54:55], v[54:55], v[222:223] op_sel_hi:[1,0]
	v_pk_mul_f32 v[52:53], v[52:53], v[222:223] op_sel_hi:[1,0]
	v_pk_mul_f32 v[50:51], v[50:51], v[222:223] op_sel_hi:[1,0]
	v_pk_mul_f32 v[48:49], v[48:49], v[222:223] op_sel_hi:[1,0]
	v_lshl_add_u64 v[250:251], v[214:215], 0, s[0:1]
	v_cvt_pk_bf16_f32 v60, v60, v61
	v_cvt_pk_bf16_f32 v61, v62, v63
	v_cvt_pk_bf16_f32 v56, v56, v57
	v_cvt_pk_bf16_f32 v57, v58, v59
	v_cvt_pk_bf16_f32 v52, v52, v53
	v_cvt_pk_bf16_f32 v53, v54, v55
	v_cvt_pk_bf16_f32 v48, v48, v49
	v_cvt_pk_bf16_f32 v49, v50, v51
	global_store_dwordx2 v[250:251], v[60:61], off
	global_store_dwordx2 v[250:251], v[56:57], off offset:512
	global_store_dwordx2 v[250:251], v[52:53], off offset:1024
	global_store_dwordx2 v[250:251], v[48:49], off offset:1536
	s_and_saveexec_b64 s[70:71], vcc
	s_cbranch_execz .LBB0_112
	global_load_dword v48, v[216:217], off
	s_waitcnt lgkmcnt(0)
	v_add_f32_e32 v56, v221, v234
	s_waitcnt lgkmcnt(0)
	v_add_f32_e32 v55, v235, v236
	v_mul_f32_e32 v56, v222, v56
	s_waitcnt lgkmcnt(0)
	v_add_f32_e32 v54, v237, v238
	v_mul_f32_e32 v55, v222, v55
	v_cndmask_b32_e64 v56, 0, v56, s[8:9]
	s_waitcnt lgkmcnt(0)
	v_add_f32_e32 v53, v239, v240
	v_mul_f32_e32 v54, v222, v54
	v_cndmask_b32_e64 v55, v56, v55, s[10:11]
	s_waitcnt lgkmcnt(0)
	v_add_f32_e32 v52, v241, v242
	v_mul_f32_e32 v53, v222, v53
	v_cndmask_b32_e64 v54, v55, v54, s[12:13]
	s_waitcnt lgkmcnt(0)
	v_add_f32_e32 v51, v243, v244
	v_mul_f32_e32 v52, v222, v52
	v_cndmask_b32_e64 v53, v54, v53, s[14:15]
	s_waitcnt lgkmcnt(0)
	v_add_f32_e32 v50, v245, v246
	v_mul_f32_e32 v51, v222, v51
	v_cndmask_b32_e64 v52, v53, v52, s[16:17]
	s_waitcnt lgkmcnt(0)
	v_add_f32_e32 v49, v247, v248
	v_mul_f32_e32 v50, v222, v50
	v_cndmask_b32_e64 v51, v52, v51, s[18:19]
	v_mul_f32_e32 v49, v222, v49
	v_cndmask_b32_e64 v50, v51, v50, s[20:21]
	v_cndmask_b32_e64 v49, v50, v49, s[22:23]
	s_lshl_b64 s[68:69], s[68:69], 5
	s_waitcnt vmcnt(0)
	v_add_f32_e32 v48, v49, v48
	v_mul_f32_e64 v49, |v48|, s35
	v_exp_f32_e32 v62, v49
	v_min_f32_e32 v63, 0, v48
	v_add_f32_e32 v50, 1.0, v62
	v_add_f32_e32 v51, -1.0, v50
	v_frexp_mant_f32_e32 v52, v50
	v_cvt_f64_f32_e32 v[48:49], v50
	v_sub_f32_e32 v53, v51, v50
	v_frexp_exp_i32_f64_e32 v48, v[48:49]
	v_cmp_gt_f32_e64 s[0:1], s41, v52
	v_sub_f32_e32 v51, v62, v51
	v_add_f32_e32 v49, 1.0, v53
	v_subbrev_co_u32_e64 v48, s[0:1], 0, v48, s[0:1]
	v_add_f32_e32 v49, v51, v49
	v_sub_u32_e32 v51, 0, v48
	v_ldexp_f32 v50, v50, v51
	v_add_f32_e32 v52, -1.0, v50
	v_add_f32_e32 v53, 1.0, v50
	v_ldexp_f32 v49, v49, v51
	v_add_f32_e32 v51, 1.0, v52
	v_add_f32_e32 v54, -1.0, v53
	v_sub_f32_e32 v51, v50, v51
	v_sub_f32_e32 v50, v50, v54
	v_add_f32_e32 v54, v49, v51
	v_add_f32_e32 v49, v49, v50
	v_add_f32_e32 v56, v53, v49
	v_rcp_f32_e32 v57, v56
	v_add_f32_e32 v51, v52, v54
	v_sub_f32_e32 v52, v51, v52
	v_sub_f32_e32 v50, v56, v53
	v_mul_f32_e32 v59, v51, v57
	v_sub_f32_e32 v58, v54, v52
	v_mul_f32_e32 v52, v56, v59
	v_sub_f32_e32 v49, v49, v50
	v_fma_f32 v54, v59, v56, -v52
	v_fmac_f32_e32 v54, v59, v49
	v_add_f32_e32 v50, v52, v54
	v_sub_f32_e32 v53, v51, v50
	v_mov_b32_e32 v55, v50
	v_pk_add_f32 v[50:51], v[50:51], v[52:53] neg_lo:[0,1] neg_hi:[0,1]
	v_cvt_f32_i32_e32 v48, v48
	v_pk_add_f32 v[50:51], v[50:51], v[54:55] neg_lo:[0,1] neg_hi:[0,1]
	v_cmp_neq_f32_e64 s[0:1], s53, v62
	v_add_f32_e32 v51, v58, v51
	v_add_f32_e32 v50, v50, v51
	v_add_f32_e32 v51, v53, v50
	v_mul_f32_e32 v55, v57, v51
	v_mul_f32_e32 v52, v56, v55
	v_sub_f32_e32 v53, v53, v51
	v_add_f32_e32 v60, v59, v55
	v_fma_f32 v54, v55, v56, -v52
	v_add_f32_e32 v58, v50, v53
	v_sub_f32_e32 v50, v60, v59
	v_fmac_f32_e32 v54, v55, v49
	v_sub_f32_e32 v49, v55, v50
	v_add_f32_e32 v50, v52, v54
	v_sub_f32_e32 v53, v51, v50
	v_mov_b32_e32 v55, v50
	v_pk_add_f32 v[50:51], v[50:51], v[52:53] neg_lo:[0,1] neg_hi:[0,1]
	s_nop 0
	v_pk_add_f32 v[50:51], v[50:51], v[54:55] neg_lo:[0,1] neg_hi:[0,1]
	s_nop 0
	v_add_f32_e32 v51, v58, v51
	v_add_f32_e32 v50, v50, v51
	v_add_f32_e32 v50, v53, v50
	v_mul_f32_e32 v50, v57, v50
	v_add_f32_e32 v49, v49, v50
	v_add_f32_e32 v50, v60, v49
	v_mul_f32_e32 v52, v50, v50
	v_sub_f32_e32 v53, v50, v60
	v_fmamk_f32 v54, v52, 0x3e9b6dac, v211
	v_sub_f32_e32 v53, v49, v53
	v_mul_f32_e32 v49, v50, v52
	v_fmaak_f32 v221, v52, v54, 0x3f2aaada
	v_ldexp_f32 v55, v53, 1
	v_pk_mul_f32 v[52:53], v[48:49], v[220:221]
	v_ldexp_f32 v51, v50, 1
	v_fma_f32 v50, v48, s52, -v52
	v_fmac_f32_e32 v50, 0xb102e308, v48
	v_pk_add_f32 v[48:49], v[52:53], v[50:51]
	v_mov_b32_e32 v54, v52
	v_sub_f32_e32 v58, v49, v51
	v_pk_add_f32 v[56:57], v[48:49], v[52:53] neg_lo:[0,1] neg_hi:[0,1]
	v_sub_f32_e32 v52, v53, v58
	v_add_f32_e32 v55, v55, v52
	v_pk_add_f32 v[52:53], v[48:49], v[54:55]
	v_mov_b32_e32 v51, v48
	v_mov_b32_e32 v57, v53
	v_pk_add_f32 v[60:61], v[50:51], v[56:57] neg_lo:[0,1] neg_hi:[0,1]
	v_pk_add_f32 v[50:51], v[50:51], v[56:57]
	v_mov_b32_e32 v59, v48
	v_pk_add_f32 v[56:57], v[50:51], v[48:49] op_sel:[1,0] op_sel_hi:[0,1] neg_lo:[0,1] neg_hi:[0,1]
	v_mov_b32_e32 v58, v55
	v_mov_b32_e32 v54, v53
	v_mov_b32_e32 v55, v51
	v_pk_mov_b32 v[48:49], v[48:49], v[56:57] op_sel:[1,0]
	v_pk_add_f32 v[52:53], v[52:53], v[56:57] op_sel_hi:[1,0] neg_lo:[0,1] neg_hi:[0,1]
	v_pk_add_f32 v[48:49], v[54:55], v[48:49] neg_lo:[0,1] neg_hi:[0,1]
	v_mov_b32_e32 v52, v60
	v_pk_add_f32 v[48:49], v[58:59], v[48:49] neg_lo:[0,1] neg_hi:[0,1]
	v_mov_b32_e32 v61, v51
	v_pk_add_f32 v[52:53], v[52:53], v[48:49]
	s_nop 0
	v_pk_add_f32 v[54:55], v[52:53], v[52:53] op_sel:[0,1] op_sel_hi:[1,0]
	s_nop 0
	v_pk_add_f32 v[50:51], v[50:51], v[54:55] op_sel:[1,0] op_sel_hi:[0,1]
	v_mov_b32_e32 v53, v50
	v_mov_b32_e32 v49, v54
	v_pk_add_f32 v[54:55], v[52:53], v[60:61] neg_lo:[0,1] neg_hi:[0,1]
	s_nop 0
	v_sub_f32_e32 v51, v52, v54
	v_pk_add_f32 v[48:49], v[48:49], v[54:55] neg_lo:[0,1] neg_hi:[0,1]
	v_sub_f32_e32 v51, v60, v51
	v_add_f32_e32 v48, v48, v51
	v_add_f32_e32 v48, v48, v49
	v_add_f32_e32 v48, v50, v48
	v_cndmask_b32_e64 v48, v231, v48, s[0:1]
	v_cmp_ngt_f32_e64 s[0:1], -1.0, v62
	s_nop 1
	v_cndmask_b32_e64 v48, v232, v48, s[0:1]
	v_cmp_neq_f32_e64 s[0:1], -1.0, v62
	s_nop 1
	v_cndmask_b32_e64 v48, v233, v48, s[0:1]
	v_cmp_lt_f32_e64 s[0:1], |v62|, s54
	s_nop 1
	v_cndmask_b32_e64 v48, v48, v62, s[0:1]
	v_sub_f32_e32 v50, v63, v48
	v_lshl_add_u64 v[48:49], v[218:219], 0, s[68:69]
	global_store_dword v[48:49], v50, off
	s_branch .LBB0_112
